# speedup vs baseline: 1.0163x; 1.0005x over previous
.LBB0_611:
	s_add_i32 s0, s36, s37
	s_cmp_ge_i32 s0, s89
	s_cbranch_scc1 .LBB0_610
	s_cmp_lt_i32 s0, s40
	s_cselect_b64 s[6:7], -1, 0
	s_and_b64 s[2:3], s[6:7], exec
	v_readlane_b32 s2, v250, 13
	v_readlane_b32 s3, v250, 14
	s_cselect_b32 s10, s28, s2
	s_cselect_b32 s2, 0, s40
	s_cselect_b32 s1, s24, s27
	s_cselect_b32 s11, s29, s3
	s_sub_i32 s2, s0, s2
	s_cmp_eq_u32 s1, 8
	s_cselect_b32 s0, 2, 3
	s_cselect_b32 s3, 3, 7
	s_lshl_b32 s1, s1, s0
	s_abs_i32 s4, s1
	v_cvt_f32_u32_e32 v3, s4
	s_sub_i32 s9, 0, s4
	s_abs_i32 s5, s2
	s_xor_b32 s8, s2, s1
	v_rcp_iflag_f32_e32 v3, v3
	s_ashr_i32 s8, s8, 31
	v_mov_b32_e32 v214, v184
	v_mul_f32_e32 v3, 0x4f7ffffe, v3
	v_cvt_u32_f32_e32 v3, v3
	v_readfirstlane_b32 s41, v214
	v_readfirstlane_b32 s12, v3
	s_mul_i32 s9, s9, s12
	s_mul_hi_u32 s9, s12, s9
	s_add_i32 s12, s12, s9
	s_mul_hi_u32 s9, s5, s12
	s_mul_i32 s12, s9, s4
	s_sub_i32 s5, s5, s12
	s_add_i32 s13, s9, 1
	s_sub_i32 s12, s5, s4
	s_cmp_ge_u32 s5, s4
	s_cselect_b32 s9, s13, s9
	s_cselect_b32 s5, s12, s5
	s_add_i32 s12, s9, 1
	s_cmp_ge_u32 s5, s4
	s_cselect_b32 s4, s12, s9
	s_xor_b32 s4, s4, s8
	s_sub_i32 s4, s4, s8
	s_mul_i32 s1, s4, s1
	s_sub_i32 s1, s2, s1
	s_lshl_b32 s2, s4, s0
	s_and_b32 s3, s1, s3
	s_add_i32 s2, s3, s2
	s_cmp_lg_u64 s[10:11], 0
	s_cselect_b64 s[8:9], -1, 0
	s_cmp_eq_u64 s[10:11], 0
	s_cbranch_scc1 .LBB0_620
	v_ashrrev_i32_e32 v222, 1, v214
	v_readlane_b32 s4, v250, 43
	v_lshl_add_u32 v224, s2, 8, v222
	v_readlane_b32 s5, v250, 44
	v_and_b32_e32 v223, 1, v214
	v_ashrrev_i32_e32 v225, 31, v224
	s_and_b64 vcc, exec, s[4:5]
	s_cbranch_vccz .Lrt_ld32
	v_lshlrev_b64 v[226:227], 5, v[224:225]
	v_lshl_add_u64 v[226:227], s[10:11], 0, v[226:227]
	v_lshlrev_b32_e32 v228, 4, v223
	v_mov_b32_e32 v229, v2
	v_lshl_add_u64 v[226:227], v[226:227], 0, v[228:229]
	global_load_dwordx4 v[226:229], v[226:227], off
	s_branch .LBB0_620
.Lrt_ld32:
	v_lshlrev_b64 v[224:225], 7, v[224:225]
	v_lshl_add_u64 v[224:225], s[10:11], 0, v[224:225]
	v_lshlrev_b32_e32 v226, 6, v223
	v_mov_b32_e32 v227, v2
	v_lshl_add_u64 v[224:225], v[224:225], 0, v[226:227]
	global_load_dwordx4 v[226:229], v[224:225], off
	global_load_dwordx4 v[230:233], v[224:225], off offset:16
	global_load_dwordx4 v[234:237], v[224:225], off offset:32
	global_load_dwordx4 v[238:241], v[224:225], off offset:48
.LBB0_620:
	s_and_b64 s[4:5], s[6:7], exec
	v_readlane_b32 s3, v250, 22
	s_cselect_b32 s19, s21, s31
	s_cselect_b32 s35, s20, s30
	s_cselect_b32 s12, s42, s3
	s_ashr_i32 s16, s41, 6
	s_lshl_b32 s33, s16, 5
	v_bfe_u32 v11, v214, 3, 3
	v_and_b32_e32 v6, 7, v214
	v_bfe_u32 v7, v214, 4, 2
	v_or_b32_e32 v3, s33, v11
	v_bitop3_b32 v8, v7, v214, 7 bitop3:0x78
	v_bitop3_b32 v6, v7, v6, 4 bitop3:0x36
	s_lshl_b32 s38, s12, 1
	s_ashr_i32 s13, s12, 31
	s_ashr_i32 s46, s1, s0
	v_lshlrev_b32_e32 v10, 4, v8
	v_mul_lo_u32 v3, v3, s38
	v_lshlrev_b32_e32 v12, 4, v6
	s_ashr_i32 s3, s2, 31
	s_lshl_b32 s4, s12, 9
	s_lshr_b64 s[0:1], s[12:13], 23
	v_cndmask_b32_e64 v5, v157, v1, s[6:7]
	v_cndmask_b32_e64 v4, v156, v0, s[6:7]
	v_add_u32_e32 v14, v3, v10
	v_add_u32_e32 v6, v12, v3
	s_mul_i32 s1, s0, s2
	s_mul_i32 s10, s4, s3
	v_mov_b32_e32 v3, s2
	s_add_i32 s1, s10, s1
	v_mad_u64_u32 v[8:9], s[10:11], s4, v3, v[4:5]
	s_ashr_i32 s47, s46, 31
	v_add_u32_e32 v9, s1, v9
	s_mul_i32 s1, s4, s47
	s_mul_hi_u32 s10, s4, s46
	s_mul_i32 s0, s0, s46
	s_add_i32 s1, s10, s1
	s_and_b32 s97, s16, 3
	s_ashr_i32 s5, s12, 6
	s_add_i32 s1, s1, s0
	s_mul_i32 s4, s4, s46
	s_add_u32 s14, s35, s4
	s_addc_u32 s15, s19, s1
	s_ashr_i32 s0, s41, 1
	s_and_b32 s18, s0, 0xffffff80
	s_lshl_b32 s0, s16, 12
	v_mov_b32_e32 v15, v2
	v_lshl_add_u64 v[162:163], v[8:9], 0, v[14:15]
	s_mov_b32 m0, s0
	s_lshl_b64 s[10:11], s[12:13], 4
	global_load_lds_dwordx4 v[162:163], off
	s_add_i32 m0, s0, 0x8000
	s_lshl_b32 s4, s97, 6
	global_load_lds_dwordx4 v14, s[14:15]
	v_lshl_add_u64 v[16:17], v[8:9], 0, s[10:11]
	v_mov_b32_e32 v7, v2
	s_or_b32 m0, s0, 0x400
	v_lshl_add_u64 v[18:19], v[16:17], 0, v[6:7]
	s_add_u32 s16, s14, s10
	global_load_lds_dwordx4 v[18:19], off
	s_addc_u32 s17, s15, s11
	s_add_i32 m0, s0, 0x8400
	s_lshl_b64 s[44:45], s[12:13], 5
	global_load_lds_dwordx4 v6, s[16:17]
	v_lshl_add_u64 v[16:17], v[16:17], 0, s[10:11]
	s_or_b32 m0, s0, 0x800
	v_lshl_add_u64 v[18:19], v[16:17], 0, v[14:15]
	s_add_u32 s16, s16, s10
	global_load_lds_dwordx4 v[18:19], off
	s_addc_u32 s17, s17, s11
	s_add_i32 m0, s0, 0x8800
	v_lshl_add_u64 v[164:165], s[14:15], 0, v[14:15]
	global_load_lds_dwordx4 v14, s[16:17]
	v_lshl_add_u64 v[14:15], v[16:17], 0, s[10:11]
	s_or_b32 m0, s0, 0xc00
	v_lshl_add_u64 v[16:17], v[14:15], 0, v[6:7]
	s_add_u32 s16, s16, s10
	global_load_lds_dwordx4 v[16:17], off
	s_addc_u32 s17, s17, s11
	s_add_i32 m0, s0, 0x8c00
	v_lshl_add_u64 v[16:17], v[162:163], 0, s[66:67]
	global_load_lds_dwordx4 v6, s[16:17]
	s_add_i32 m0, s0, 0x10000
	s_nop 0
	global_load_lds_dwordx4 v[16:17], off
	s_add_i32 m0, s0, 0x18000
	s_sub_u32 s44, 0, s44
	v_lshl_add_u64 v[16:17], v[164:165], 0, s[66:67]
	s_subb_u32 s45, 0, s45
	global_load_lds_dwordx4 v[16:17], off
	v_lshl_add_u64 v[14:15], v[14:15], 0, s[44:45]
	s_add_i32 m0, s0, 0x10400
	v_lshl_add_u64 v[14:15], v[14:15], 0, v[6:7]
	s_add_u32 s16, s16, s44
	v_lshl_add_u64 v[14:15], v[14:15], 0, s[66:67]
	s_addc_u32 s17, s17, s45
	global_load_lds_dwordx4 v[14:15], off
	v_lshl_add_u64 v[14:15], s[16:17], 0, v[6:7]
	v_lshl_add_u64 v[14:15], v[14:15], 0, s[66:67]
	s_add_i32 m0, s0, 0x18400
	v_and_b32_e32 v3, 31, v214
	global_load_lds_dwordx4 v[14:15], off
	s_and_b64 vcc, exec, s[8:9]
	s_cbranch_vccz .Lrt_done
	v_readlane_b32 s98, v250, 43
	v_readlane_b32 s99, v250, 44
	s_nop 3
	s_and_b64 vcc, exec, s[98:99]
	s_waitcnt vmcnt(12)
	s_cbranch_vccz .Lrt_sum32
	v_add_f32_e32 v226, v226, v227
	v_add_f32_e32 v226, v228, v226
	v_add_f32_e32 v226, v229, v226
	s_branch .Lrt_fin
.Lrt_sum32:
	v_add_f32_e32 v226, v226, v227
	v_add_f32_e32 v230, v230, v231
	v_add_f32_e32 v234, v234, v235
	v_add_f32_e32 v238, v238, v239
	v_add_f32_e32 v226, v228, v226
	v_add_f32_e32 v230, v232, v230
	v_add_f32_e32 v234, v236, v234
	v_add_f32_e32 v238, v240, v238
	v_add_f32_e32 v226, v229, v226
	v_add_f32_e32 v230, v233, v230
	v_add_f32_e32 v234, v237, v234
	v_add_f32_e32 v238, v241, v238
	v_add_f32_e32 v226, v226, v230
	v_add_f32_e32 v226, v226, v234
	v_add_f32_e32 v226, v226, v238
.Lrt_fin:
	v_readlane_b32 s98, v250, 19
	v_lshl_add_u32 v222, v222, 2, v211
	s_nop 1
	v_mov_b32_dpp v227, v226 quad_perm:[1,0,3,2] row_mask:0xf bank_mask:0xf bound_ctrl:1
	v_mov_b32_e32 v228, s98
	v_cmp_eq_u32_e32 vcc, 0, v223
	s_and_saveexec_b64 s[98:99], vcc
	s_cbranch_execz .Lrt_skipw
	v_add_f32_e32 v227, v226, v227
	s_nop 0
	v_fma_f32 v227, v228, v227, v186
	v_mul_f32_e32 v229, 0x4b800000, v227
	v_cmp_gt_f32_e32 vcc, s60, v227
	s_nop 1
	v_cndmask_b32_e32 v227, v227, v229, vcc
	v_rsq_f32_e32 v227, v227
	s_nop 0
	v_mul_f32_e32 v229, 0x45800000, v227
	v_cndmask_b32_e32 v227, v227, v229, vcc
	ds_write_b32 v222, v227
.Lrt_skipw:
	s_or_b64 exec, exec, s[98:99]
.Lrt_done:
	s_waitcnt vmcnt(4) lgkmcnt(0)
	s_barrier
	v_bfe_u32 v213, v214, 5, 1
	v_lshrrev_b32_e32 v14, 1, v214
	v_or_b32_e32 v13, s18, v3
	v_or_b32_e32 v15, s4, v3
	v_bitop3_b32 v14, v14, v213, 7 bitop3:0x6c
	v_lshlrev_b32_e32 v179, 7, v15
	v_lshlrev_b32_e32 v178, 7, v13
	v_lshlrev_b32_e32 v14, 4, v14
	v_or_b32_e32 v183, v179, v14
	v_and_b32_e32 v246, 15, v214
	v_bfe_u32 v247, v214, 4, 2
	v_and_b32_e32 v248, 3, v246
	v_and_b32_e32 v249, 4, v246
	v_lshl_or_b32 v248, v249, 1, v248
	v_and_b32_e32 v249, 8, v246
	v_lshrrev_b32_e32 v249, 1, v249
	v_or_b32_e32 v248, v248, v249
	v_lshrrev_b32_e32 v249, 1, v248
	v_xor_b32_e32 v249, v249, v247
	v_lshlrev_b32_e32 v249, 4, v249
	v_lshl_or_b32 v249, v248, 7, v249
	s_lshl_b32 s16, s18, 7
	v_or_b32_e32 v215, s16, v249
	v_lshrrev_b32_e32 v249, 1, v246
	v_xor_b32_e32 v249, v249, v247
	v_lshlrev_b32_e32 v249, 4, v249
	v_lshl_or_b32 v249, v246, 7, v249
	s_lshl_b32 s16, s4, 7
	s_or_b32 s16, s16, 0x8000
	v_or_b32_e32 v216, s16, v249
	ds_read_b128 v[132:135], v216
	ds_read_b128 v[136:139], v216 offset:2048
	ds_read_b128 v[140:143], v216 offset:4096
	ds_read_b128 v[144:147], v216 offset:6144
	ds_read_b128 v[148:151], v215
	ds_read_b128 v[152:155], v215 offset:2048
	ds_read_b128 v[238:241], v215 offset:4096
	ds_read_b128 v[242:245], v215 offset:6144
	v_bfe_u32 v13, v214, 1, 3
	v_bitop3_b32 v14, v213, v13, 4 bitop3:0x36
	v_bitop3_b32 v15, v213, v13, 6 bitop3:0x36
	s_cmp_gt_i32 s5, 1
	s_mov_b64 s[16:17], -1
	v_lshlrev_b32_e32 v182, 4, v14
	v_lshlrev_b32_e32 v181, 4, v15
	s_cbranch_scc1 .LBB0_622
	v_lshlrev_b32_e32 v166, 4, v14
	v_lshlrev_b32_e32 v167, 4, v15
	s_mov_b64 s[16:17], 0

.LBB0_1217:
	s_and_b64 vcc, exec, s[18:19]
	s_cbranch_vccz .LBB0_609
	s_lshl_b32 s0, s47, 2
	v_mul_i32_i24_e32 v132, s0, v213
	v_add_lshl_u32 v132, v132, v3, 1
	v_mov_b32_e32 v133, v2
	s_lshl_b32 s0, s46, 7
	s_lshl_b32 s1, s97, 5
	s_or_b32 s2, s1, s0
	s_ashr_i32 s3, s2, 31
	v_lshl_add_u64 v[132:133], s[48:49], 0, v[132:133]
	s_add_u32 s0, s88, s2
	s_addc_u32 s1, s43, s3
	v_mov_b32_e32 v222, 0xbfb8aa3b
	v_mov_b32_e32 v223, 0xbfb8aa3b
	v_mov_b32_e32 v224, 1.0
	v_mov_b32_e32 v225, 1.0
	v_lshl_add_u64 v[236:237], s[0:1], 1, v[132:133]
	s_lshl_b32 s0, s47, 1
	s_mov_b32 s1, 0
	s_mul_i32 s2, s47, 10
	s_mov_b32 s3, 0
	v_pk_mul_f32 v[226:227], v[100:101], v[222:223]
	v_pk_mul_f32 v[228:229], v[102:103], v[222:223]
	v_exp_f32_e32 v226, v226
	v_exp_f32_e32 v227, v227
	v_exp_f32_e32 v228, v228
	v_exp_f32_e32 v229, v229
	v_lshl_add_u64 v[238:239], s[0:1], 0, v[236:237]
	v_pk_add_f32 v[226:227], v[226:227], v[224:225]
	v_pk_add_f32 v[228:229], v[228:229], v[224:225]
	v_rcp_f32_e32 v226, v226
	v_rcp_f32_e32 v227, v227
	v_rcp_f32_e32 v228, v228
	v_rcp_f32_e32 v229, v229
	v_lshl_add_u64 v[240:241], s[0:1], 0, v[238:239]
	v_pk_mul_f32 v[226:227], v[100:101], v[226:227]
	v_pk_mul_f32 v[228:229], v[102:103], v[228:229]
	v_lshl_add_u64 v[242:243], s[0:1], 0, v[240:241]
	v_pk_mul_f32 v[226:227], v[116:117], v[226:227]
	v_pk_mul_f32 v[228:229], v[118:119], v[228:229]
	v_cvt_pk_bf16_f32 v234, v226, v227
	v_cvt_pk_bf16_f32 v235, v228, v229
	global_store_short v[236:237], v234, off nt
	global_store_short_d16_hi v[238:239], v234, off nt
	global_store_short v[240:241], v235, off nt
	global_store_short_d16_hi v[242:243], v235, off nt
	v_lshl_add_u64 v[236:237], s[2:3], 0, v[242:243]
	v_pk_mul_f32 v[230:231], v[104:105], v[222:223]
	v_pk_mul_f32 v[232:233], v[106:107], v[222:223]
	v_exp_f32_e32 v230, v230
	v_exp_f32_e32 v231, v231
	v_exp_f32_e32 v232, v232
	v_exp_f32_e32 v233, v233
	v_lshl_add_u64 v[238:239], s[0:1], 0, v[236:237]
	v_pk_add_f32 v[230:231], v[230:231], v[224:225]
	v_pk_add_f32 v[232:233], v[232:233], v[224:225]
	v_rcp_f32_e32 v230, v230
	v_rcp_f32_e32 v231, v231
	v_rcp_f32_e32 v232, v232
	v_rcp_f32_e32 v233, v233
	v_lshl_add_u64 v[240:241], s[0:1], 0, v[238:239]
	v_pk_mul_f32 v[230:231], v[104:105], v[230:231]
	v_pk_mul_f32 v[232:233], v[106:107], v[232:233]
	v_lshl_add_u64 v[242:243], s[0:1], 0, v[240:241]
	v_pk_mul_f32 v[230:231], v[120:121], v[230:231]
	v_pk_mul_f32 v[232:233], v[122:123], v[232:233]
	v_cvt_pk_bf16_f32 v244, v230, v231
	v_cvt_pk_bf16_f32 v245, v232, v233
	global_store_short v[236:237], v244, off nt
	global_store_short_d16_hi v[238:239], v244, off nt
	global_store_short v[240:241], v245, off nt
	global_store_short_d16_hi v[242:243], v245, off nt
	v_lshl_add_u64 v[236:237], s[2:3], 0, v[242:243]
	v_pk_mul_f32 v[226:227], v[108:109], v[222:223]
	v_pk_mul_f32 v[228:229], v[110:111], v[222:223]
	v_exp_f32_e32 v226, v226
	v_exp_f32_e32 v227, v227
	v_exp_f32_e32 v228, v228
	v_exp_f32_e32 v229, v229
	v_lshl_add_u64 v[238:239], s[0:1], 0, v[236:237]
	v_pk_add_f32 v[226:227], v[226:227], v[224:225]
	v_pk_add_f32 v[228:229], v[228:229], v[224:225]
	v_rcp_f32_e32 v226, v226
	v_rcp_f32_e32 v227, v227
	v_rcp_f32_e32 v228, v228
	v_rcp_f32_e32 v229, v229
	v_lshl_add_u64 v[240:241], s[0:1], 0, v[238:239]
	v_pk_mul_f32 v[226:227], v[108:109], v[226:227]
	v_pk_mul_f32 v[228:229], v[110:111], v[228:229]
	v_lshl_add_u64 v[242:243], s[0:1], 0, v[240:241]
	v_pk_mul_f32 v[226:227], v[124:125], v[226:227]
	v_pk_mul_f32 v[228:229], v[126:127], v[228:229]
	v_cvt_pk_bf16_f32 v234, v226, v227
	v_cvt_pk_bf16_f32 v235, v228, v229
	global_store_short v[236:237], v234, off nt
	global_store_short_d16_hi v[238:239], v234, off nt
	global_store_short v[240:241], v235, off nt
	global_store_short_d16_hi v[242:243], v235, off nt
	v_lshl_add_u64 v[236:237], s[2:3], 0, v[242:243]
	v_pk_mul_f32 v[230:231], v[112:113], v[222:223]
	v_pk_mul_f32 v[232:233], v[114:115], v[222:223]
	v_exp_f32_e32 v230, v230
	v_exp_f32_e32 v231, v231
	v_exp_f32_e32 v232, v232
	v_exp_f32_e32 v233, v233
	v_lshl_add_u64 v[238:239], s[0:1], 0, v[236:237]
	v_pk_add_f32 v[230:231], v[230:231], v[224:225]
	v_pk_add_f32 v[232:233], v[232:233], v[224:225]
	v_rcp_f32_e32 v230, v230
	v_rcp_f32_e32 v231, v231
	v_rcp_f32_e32 v232, v232
	v_rcp_f32_e32 v233, v233
	v_lshl_add_u64 v[240:241], s[0:1], 0, v[238:239]
	v_pk_mul_f32 v[230:231], v[112:113], v[230:231]
	v_pk_mul_f32 v[232:233], v[114:115], v[232:233]
	v_lshl_add_u64 v[242:243], s[0:1], 0, v[240:241]
	v_pk_mul_f32 v[230:231], v[128:129], v[230:231]
	v_pk_mul_f32 v[232:233], v[130:131], v[232:233]
	v_cvt_pk_bf16_f32 v244, v230, v231
	v_cvt_pk_bf16_f32 v245, v232, v233
	global_store_short v[236:237], v244, off nt
	global_store_short_d16_hi v[238:239], v244, off nt
	global_store_short v[240:241], v245, off nt
	global_store_short_d16_hi v[242:243], v245, off nt
	v_lshl_add_u64 v[236:237], s[2:3], 0, v[242:243]
	v_pk_mul_f32 v[226:227], v[84:85], v[222:223]
	v_pk_mul_f32 v[228:229], v[86:87], v[222:223]
	v_exp_f32_e32 v226, v226
	v_exp_f32_e32 v227, v227
	v_exp_f32_e32 v228, v228
	v_exp_f32_e32 v229, v229
	v_lshl_add_u64 v[238:239], s[0:1], 0, v[236:237]
	v_pk_add_f32 v[226:227], v[226:227], v[224:225]
	v_pk_add_f32 v[228:229], v[228:229], v[224:225]
	v_rcp_f32_e32 v226, v226
	v_rcp_f32_e32 v227, v227
	v_rcp_f32_e32 v228, v228
	v_rcp_f32_e32 v229, v229
	v_lshl_add_u64 v[240:241], s[0:1], 0, v[238:239]
	v_pk_mul_f32 v[226:227], v[84:85], v[226:227]
	v_pk_mul_f32 v[228:229], v[86:87], v[228:229]
	v_lshl_add_u64 v[242:243], s[0:1], 0, v[240:241]
	v_pk_mul_f32 v[226:227], v[68:69], v[226:227]
	v_pk_mul_f32 v[228:229], v[70:71], v[228:229]
	v_cvt_pk_bf16_f32 v234, v226, v227
	v_cvt_pk_bf16_f32 v235, v228, v229
	global_store_short v[236:237], v234, off nt
	global_store_short_d16_hi v[238:239], v234, off nt
	global_store_short v[240:241], v235, off nt
	global_store_short_d16_hi v[242:243], v235, off nt
	v_lshl_add_u64 v[236:237], s[2:3], 0, v[242:243]
	v_pk_mul_f32 v[230:231], v[88:89], v[222:223]
	v_pk_mul_f32 v[232:233], v[90:91], v[222:223]
	v_exp_f32_e32 v230, v230
	v_exp_f32_e32 v231, v231
	v_exp_f32_e32 v232, v232
	v_exp_f32_e32 v233, v233
	v_lshl_add_u64 v[238:239], s[0:1], 0, v[236:237]
	v_pk_add_f32 v[230:231], v[230:231], v[224:225]
	v_pk_add_f32 v[232:233], v[232:233], v[224:225]
	v_rcp_f32_e32 v230, v230
	v_rcp_f32_e32 v231, v231
	v_rcp_f32_e32 v232, v232
	v_rcp_f32_e32 v233, v233
	v_lshl_add_u64 v[240:241], s[0:1], 0, v[238:239]
	v_pk_mul_f32 v[230:231], v[88:89], v[230:231]
	v_pk_mul_f32 v[232:233], v[90:91], v[232:233]
	v_lshl_add_u64 v[242:243], s[0:1], 0, v[240:241]
	v_pk_mul_f32 v[230:231], v[72:73], v[230:231]
	v_pk_mul_f32 v[232:233], v[74:75], v[232:233]
	v_cvt_pk_bf16_f32 v244, v230, v231
	v_cvt_pk_bf16_f32 v245, v232, v233
	global_store_short v[236:237], v244, off nt
	global_store_short_d16_hi v[238:239], v244, off nt
	global_store_short v[240:241], v245, off nt
	global_store_short_d16_hi v[242:243], v245, off nt
	v_lshl_add_u64 v[236:237], s[2:3], 0, v[242:243]
	v_pk_mul_f32 v[226:227], v[92:93], v[222:223]
	v_pk_mul_f32 v[228:229], v[94:95], v[222:223]
	v_exp_f32_e32 v226, v226
	v_exp_f32_e32 v227, v227
	v_exp_f32_e32 v228, v228
	v_exp_f32_e32 v229, v229
	v_lshl_add_u64 v[238:239], s[0:1], 0, v[236:237]
	v_pk_add_f32 v[226:227], v[226:227], v[224:225]
	v_pk_add_f32 v[228:229], v[228:229], v[224:225]
	v_rcp_f32_e32 v226, v226
	v_rcp_f32_e32 v227, v227
	v_rcp_f32_e32 v228, v228
	v_rcp_f32_e32 v229, v229
	v_lshl_add_u64 v[240:241], s[0:1], 0, v[238:239]
	v_pk_mul_f32 v[226:227], v[92:93], v[226:227]
	v_pk_mul_f32 v[228:229], v[94:95], v[228:229]
	v_lshl_add_u64 v[242:243], s[0:1], 0, v[240:241]
	v_pk_mul_f32 v[226:227], v[76:77], v[226:227]
	v_pk_mul_f32 v[228:229], v[78:79], v[228:229]
	v_cvt_pk_bf16_f32 v234, v226, v227
	v_cvt_pk_bf16_f32 v235, v228, v229
	global_store_short v[236:237], v234, off nt
	global_store_short_d16_hi v[238:239], v234, off nt
	global_store_short v[240:241], v235, off nt
	global_store_short_d16_hi v[242:243], v235, off nt
	v_lshl_add_u64 v[236:237], s[2:3], 0, v[242:243]
	v_pk_mul_f32 v[230:231], v[96:97], v[222:223]
	v_pk_mul_f32 v[232:233], v[98:99], v[222:223]
	v_exp_f32_e32 v230, v230
	v_exp_f32_e32 v231, v231
	v_exp_f32_e32 v232, v232
	v_exp_f32_e32 v233, v233
	v_lshl_add_u64 v[238:239], s[0:1], 0, v[236:237]
	v_pk_add_f32 v[230:231], v[230:231], v[224:225]
	v_pk_add_f32 v[232:233], v[232:233], v[224:225]
	v_rcp_f32_e32 v230, v230
	v_rcp_f32_e32 v231, v231
	v_rcp_f32_e32 v232, v232
	v_rcp_f32_e32 v233, v233
	v_lshl_add_u64 v[240:241], s[0:1], 0, v[238:239]
	v_pk_mul_f32 v[230:231], v[96:97], v[230:231]
	v_pk_mul_f32 v[232:233], v[98:99], v[232:233]
	v_lshl_add_u64 v[242:243], s[0:1], 0, v[240:241]
	v_pk_mul_f32 v[230:231], v[80:81], v[230:231]
	v_pk_mul_f32 v[232:233], v[82:83], v[232:233]
	v_cvt_pk_bf16_f32 v244, v230, v231
	v_cvt_pk_bf16_f32 v245, v232, v233
	global_store_short v[236:237], v244, off nt
	global_store_short_d16_hi v[238:239], v244, off nt
	global_store_short v[240:241], v245, off nt
	global_store_short_d16_hi v[242:243], v245, off nt
	v_lshl_add_u64 v[236:237], s[2:3], 0, v[242:243]
	v_pk_mul_f32 v[226:227], v[52:53], v[222:223]
	v_pk_mul_f32 v[228:229], v[54:55], v[222:223]
	v_exp_f32_e32 v226, v226
	v_exp_f32_e32 v227, v227
	v_exp_f32_e32 v228, v228
	v_exp_f32_e32 v229, v229
	v_lshl_add_u64 v[238:239], s[0:1], 0, v[236:237]
	v_pk_add_f32 v[226:227], v[226:227], v[224:225]
	v_pk_add_f32 v[228:229], v[228:229], v[224:225]
	v_rcp_f32_e32 v226, v226
	v_rcp_f32_e32 v227, v227
	v_rcp_f32_e32 v228, v228
	v_rcp_f32_e32 v229, v229
	v_lshl_add_u64 v[240:241], s[0:1], 0, v[238:239]
	v_pk_mul_f32 v[226:227], v[52:53], v[226:227]
	v_pk_mul_f32 v[228:229], v[54:55], v[228:229]
	v_lshl_add_u64 v[242:243], s[0:1], 0, v[240:241]
	v_pk_mul_f32 v[226:227], v[36:37], v[226:227]
	v_pk_mul_f32 v[228:229], v[38:39], v[228:229]
	v_cvt_pk_bf16_f32 v234, v226, v227
	v_cvt_pk_bf16_f32 v235, v228, v229
	global_store_short v[236:237], v234, off nt
	global_store_short_d16_hi v[238:239], v234, off nt
	global_store_short v[240:241], v235, off nt
	global_store_short_d16_hi v[242:243], v235, off nt
	v_lshl_add_u64 v[236:237], s[2:3], 0, v[242:243]
	v_pk_mul_f32 v[230:231], v[56:57], v[222:223]
	v_pk_mul_f32 v[232:233], v[58:59], v[222:223]
	v_exp_f32_e32 v230, v230
	v_exp_f32_e32 v231, v231
	v_exp_f32_e32 v232, v232
	v_exp_f32_e32 v233, v233
	v_lshl_add_u64 v[238:239], s[0:1], 0, v[236:237]
	v_pk_add_f32 v[230:231], v[230:231], v[224:225]
	v_pk_add_f32 v[232:233], v[232:233], v[224:225]
	v_rcp_f32_e32 v230, v230
	v_rcp_f32_e32 v231, v231
	v_rcp_f32_e32 v232, v232
	v_rcp_f32_e32 v233, v233
	v_lshl_add_u64 v[240:241], s[0:1], 0, v[238:239]
	v_pk_mul_f32 v[230:231], v[56:57], v[230:231]
	v_pk_mul_f32 v[232:233], v[58:59], v[232:233]
	v_lshl_add_u64 v[242:243], s[0:1], 0, v[240:241]
	v_pk_mul_f32 v[230:231], v[40:41], v[230:231]
	v_pk_mul_f32 v[232:233], v[42:43], v[232:233]
	v_cvt_pk_bf16_f32 v244, v230, v231
	v_cvt_pk_bf16_f32 v245, v232, v233
	global_store_short v[236:237], v244, off nt
	global_store_short_d16_hi v[238:239], v244, off nt
	global_store_short v[240:241], v245, off nt
	global_store_short_d16_hi v[242:243], v245, off nt
	v_lshl_add_u64 v[236:237], s[2:3], 0, v[242:243]
	v_pk_mul_f32 v[226:227], v[60:61], v[222:223]
	v_pk_mul_f32 v[228:229], v[62:63], v[222:223]
	v_exp_f32_e32 v226, v226
	v_exp_f32_e32 v227, v227
	v_exp_f32_e32 v228, v228
	v_exp_f32_e32 v229, v229
	v_lshl_add_u64 v[238:239], s[0:1], 0, v[236:237]
	v_pk_add_f32 v[226:227], v[226:227], v[224:225]
	v_pk_add_f32 v[228:229], v[228:229], v[224:225]
	v_rcp_f32_e32 v226, v226
	v_rcp_f32_e32 v227, v227
	v_rcp_f32_e32 v228, v228
	v_rcp_f32_e32 v229, v229
	v_lshl_add_u64 v[240:241], s[0:1], 0, v[238:239]
	v_pk_mul_f32 v[226:227], v[60:61], v[226:227]
	v_pk_mul_f32 v[228:229], v[62:63], v[228:229]
	v_lshl_add_u64 v[242:243], s[0:1], 0, v[240:241]
	v_pk_mul_f32 v[226:227], v[44:45], v[226:227]
	v_pk_mul_f32 v[228:229], v[46:47], v[228:229]
	v_cvt_pk_bf16_f32 v234, v226, v227
	v_cvt_pk_bf16_f32 v235, v228, v229
	global_store_short v[236:237], v234, off nt
	global_store_short_d16_hi v[238:239], v234, off nt
	global_store_short v[240:241], v235, off nt
	global_store_short_d16_hi v[242:243], v235, off nt
	v_lshl_add_u64 v[236:237], s[2:3], 0, v[242:243]
	v_pk_mul_f32 v[230:231], v[64:65], v[222:223]
	v_pk_mul_f32 v[232:233], v[66:67], v[222:223]
	v_exp_f32_e32 v230, v230
	v_exp_f32_e32 v231, v231
	v_exp_f32_e32 v232, v232
	v_exp_f32_e32 v233, v233
	v_lshl_add_u64 v[238:239], s[0:1], 0, v[236:237]
	v_pk_add_f32 v[230:231], v[230:231], v[224:225]
	v_pk_add_f32 v[232:233], v[232:233], v[224:225]
	v_rcp_f32_e32 v230, v230
	v_rcp_f32_e32 v231, v231
	v_rcp_f32_e32 v232, v232
	v_rcp_f32_e32 v233, v233
	v_lshl_add_u64 v[240:241], s[0:1], 0, v[238:239]
	v_pk_mul_f32 v[230:231], v[64:65], v[230:231]
	v_pk_mul_f32 v[232:233], v[66:67], v[232:233]
	v_lshl_add_u64 v[242:243], s[0:1], 0, v[240:241]
	v_pk_mul_f32 v[230:231], v[48:49], v[230:231]
	v_pk_mul_f32 v[232:233], v[50:51], v[232:233]
	v_cvt_pk_bf16_f32 v244, v230, v231
	v_cvt_pk_bf16_f32 v245, v232, v233
	global_store_short v[236:237], v244, off nt
	global_store_short_d16_hi v[238:239], v244, off nt
	global_store_short v[240:241], v245, off nt
	global_store_short_d16_hi v[242:243], v245, off nt
	v_lshl_add_u64 v[236:237], s[2:3], 0, v[242:243]
	v_pk_mul_f32 v[226:227], v[20:21], v[222:223]
	v_pk_mul_f32 v[228:229], v[22:23], v[222:223]
	v_exp_f32_e32 v226, v226
	v_exp_f32_e32 v227, v227
	v_exp_f32_e32 v228, v228
	v_exp_f32_e32 v229, v229
	v_lshl_add_u64 v[238:239], s[0:1], 0, v[236:237]
	v_pk_add_f32 v[226:227], v[226:227], v[224:225]
	v_pk_add_f32 v[228:229], v[228:229], v[224:225]
	v_rcp_f32_e32 v226, v226
	v_rcp_f32_e32 v227, v227
	v_rcp_f32_e32 v228, v228
	v_rcp_f32_e32 v229, v229
	v_lshl_add_u64 v[240:241], s[0:1], 0, v[238:239]
	v_pk_mul_f32 v[226:227], v[20:21], v[226:227]
	v_pk_mul_f32 v[228:229], v[22:23], v[228:229]
	v_lshl_add_u64 v[242:243], s[0:1], 0, v[240:241]
	v_pk_mul_f32 v[226:227], v[4:5], v[226:227]
	v_pk_mul_f32 v[228:229], v[6:7], v[228:229]
	v_cvt_pk_bf16_f32 v234, v226, v227
	v_cvt_pk_bf16_f32 v235, v228, v229
	global_store_short v[236:237], v234, off nt
	global_store_short_d16_hi v[238:239], v234, off nt
	global_store_short v[240:241], v235, off nt
	global_store_short_d16_hi v[242:243], v235, off nt
	v_lshl_add_u64 v[236:237], s[2:3], 0, v[242:243]
	v_pk_mul_f32 v[230:231], v[24:25], v[222:223]
	v_pk_mul_f32 v[232:233], v[26:27], v[222:223]
	v_exp_f32_e32 v230, v230
	v_exp_f32_e32 v231, v231
	v_exp_f32_e32 v232, v232
	v_exp_f32_e32 v233, v233
	v_lshl_add_u64 v[238:239], s[0:1], 0, v[236:237]
	v_pk_add_f32 v[230:231], v[230:231], v[224:225]
	v_pk_add_f32 v[232:233], v[232:233], v[224:225]
	v_rcp_f32_e32 v230, v230
	v_rcp_f32_e32 v231, v231
	v_rcp_f32_e32 v232, v232
	v_rcp_f32_e32 v233, v233
	v_lshl_add_u64 v[240:241], s[0:1], 0, v[238:239]
	v_pk_mul_f32 v[230:231], v[24:25], v[230:231]
	v_pk_mul_f32 v[232:233], v[26:27], v[232:233]
	v_lshl_add_u64 v[242:243], s[0:1], 0, v[240:241]
	v_pk_mul_f32 v[230:231], v[8:9], v[230:231]
	v_pk_mul_f32 v[232:233], v[10:11], v[232:233]
	v_cvt_pk_bf16_f32 v244, v230, v231
	v_cvt_pk_bf16_f32 v245, v232, v233
	global_store_short v[236:237], v244, off nt
	global_store_short_d16_hi v[238:239], v244, off nt
	global_store_short v[240:241], v245, off nt
	global_store_short_d16_hi v[242:243], v245, off nt
	v_lshl_add_u64 v[236:237], s[2:3], 0, v[242:243]
	v_pk_mul_f32 v[226:227], v[28:29], v[222:223]
	v_pk_mul_f32 v[228:229], v[30:31], v[222:223]
	v_exp_f32_e32 v226, v226
	v_exp_f32_e32 v227, v227
	v_exp_f32_e32 v228, v228
	v_exp_f32_e32 v229, v229
	v_lshl_add_u64 v[238:239], s[0:1], 0, v[236:237]
	v_pk_add_f32 v[226:227], v[226:227], v[224:225]
	v_pk_add_f32 v[228:229], v[228:229], v[224:225]
	v_rcp_f32_e32 v226, v226
	v_rcp_f32_e32 v227, v227
	v_rcp_f32_e32 v228, v228
	v_rcp_f32_e32 v229, v229
	v_lshl_add_u64 v[240:241], s[0:1], 0, v[238:239]
	v_pk_mul_f32 v[226:227], v[28:29], v[226:227]
	v_pk_mul_f32 v[228:229], v[30:31], v[228:229]
	v_lshl_add_u64 v[242:243], s[0:1], 0, v[240:241]
	v_pk_mul_f32 v[226:227], v[12:13], v[226:227]
	v_pk_mul_f32 v[228:229], v[14:15], v[228:229]
	v_cvt_pk_bf16_f32 v234, v226, v227
	v_cvt_pk_bf16_f32 v235, v228, v229
	global_store_short v[236:237], v234, off nt
	global_store_short_d16_hi v[238:239], v234, off nt
	global_store_short v[240:241], v235, off nt
	global_store_short_d16_hi v[242:243], v235, off nt
	v_lshl_add_u64 v[236:237], s[2:3], 0, v[242:243]
	v_pk_mul_f32 v[230:231], v[32:33], v[222:223]
	v_pk_mul_f32 v[232:233], v[34:35], v[222:223]
	v_exp_f32_e32 v230, v230
	v_exp_f32_e32 v231, v231
	v_exp_f32_e32 v232, v232
	v_exp_f32_e32 v233, v233
	v_lshl_add_u64 v[238:239], s[0:1], 0, v[236:237]
	v_pk_add_f32 v[230:231], v[230:231], v[224:225]
	v_pk_add_f32 v[232:233], v[232:233], v[224:225]
	v_rcp_f32_e32 v230, v230
	v_rcp_f32_e32 v231, v231
	v_rcp_f32_e32 v232, v232
	v_rcp_f32_e32 v233, v233
	v_lshl_add_u64 v[240:241], s[0:1], 0, v[238:239]
	v_pk_mul_f32 v[230:231], v[32:33], v[230:231]
	v_pk_mul_f32 v[232:233], v[34:35], v[232:233]
	v_lshl_add_u64 v[242:243], s[0:1], 0, v[240:241]
	v_pk_mul_f32 v[230:231], v[16:17], v[230:231]
	v_pk_mul_f32 v[232:233], v[18:19], v[232:233]
	v_cvt_pk_bf16_f32 v244, v230, v231
	v_cvt_pk_bf16_f32 v245, v232, v233
	global_store_short v[236:237], v244, off nt
	global_store_short_d16_hi v[238:239], v244, off nt
	global_store_short v[240:241], v245, off nt
	global_store_short_d16_hi v[242:243], v245, off nt
	s_branch .LBB0_609
